# v3 plus instruction selection in the GEMM3 epilogue: never-taken denormal range guards around the 8 v_rsq per tile removed (argument is mean+1e-6), bit-identical
# baseline (speedup 1.0000x reference)
; #define LAS __attribute__((address_space(3)))
; DEV u32x4 pack8(const float (&v)[8]) { u32x4 w; w.x = cvt_pk_bf16(v[0], v[1]); w.y = cvt_pk_bf16(v[2], v[3]); w.z = cvt_pk_bf16(v[4], v[5]); w.w = cvt_pk_bf16(v[6], v[7]); return w; }
; DEV void TileMap::operator()(int t, int& brow, int& bcol) const { int pm, pn; tile_map(t, nM, nN, pm, pn); brow = pm * 256; bcol = pn * 256; }
; DEV void TileG1::operator()(int t, int& brow, int& bcol) const { int pm, pn; tile_map(t, 192, 7, pm, pn); brow = pm * 256; bcol = (pn == 0 ? 6 : pn - 1) * 256; }
; DEV void TileMapRev::operator()(int t, int& brow, int& bcol) const { int pm, pn; tile_map(t, nM, nN, pm, pn); brow = (nM - 1 - pm) * 256; bcol = pn * 256; }
;     DEV void operator()(f32x4 (&acc)[2][2][4][2], int brow, int bcol, LAS unsigned char* lds, int par) const {
;         EPI_IDS
; #pragma unroll
;         for (int ai = 0; ai < 2; ++ai)
; #pragma unroll
;             for (int m = 0; m < 4; ++m) {
;                 const int lr = ai * 128 + wr * 64 + m * 16 + fr, row = brow + lr;
;                 const f32x4 s4 = *(const LAS f32x4*)(lds + LDS_EX + par * 4096 + lr * 16);
;                 const float rs = rsqrtf(((s4[0] + s4[1]) + (s4[2] + s4[3])) * (1.0f / 1024.0f) + EPS);
;                 float o[8];
;                 const float rs2 = rs * rs, ce = rs * -1.4426950408889634f;
; #pragma unroll
;                 for (int bj = 0; bj < 2; ++bj) {
;                     const f32x4 g = acc[ai][bj][m][0], u = acc[ai][bj][m][1];
; #pragma unroll
;                     for (int j = 0; j < 4; ++j) o[bj * 4 + j] = (g[j] * u[j]) * rs2 * __builtin_amdgcn_rcpf(1.0f + __builtin_amdgcn_exp2f(g[j] * ce));
;                 }
;                 *(u32x4*)(act + (size_t)row * DFF + (bcol >> 1) + wc * 32 + fq * 8) = pack8(o);
;             }
.LBB0_1341:
	s_or_b64 exec, exec, s[8:9]
	v_mov_b32_e32 v137, v188
	s_movk_i32 s8, 0xffc0
	v_and_b32_e32 v136, 15, v137
	v_ashrrev_i32_e32 v138, 2, v137
	v_and_or_b32 v136, v138, s8, v136
	s_lshl_b32 s8, s4, 12
	s_add_i32 s8, s8, 0
	s_add_i32 s8, s8, 0x20000
	v_lshl_add_u32 v138, v136, 4, s8
	ds_read_b128 v[158:161], v138
	v_mul_f32_e32 v120, v124, v120
	v_mul_f32_e32 v121, v125, v121
	v_mul_f32_e32 v122, v126, v122
	v_mul_f32_e32 v123, v127, v123
	s_waitcnt lgkmcnt(0)
	v_mov_b32_e32 v138, v159
	v_mov_b32_e32 v139, v160
	v_mov_b32_e32 v159, v161
	v_pk_add_f32 v[138:139], v[138:139], v[158:159]
	v_mul_f32_e32 v159, v116, v112
	v_add_f32_e32 v138, v138, v139
	v_fmamk_f32 v138, v138, 0x3a800000, v189
	v_mul_f32_e32 v160, v117, v113
	v_rsq_f32_e32 v138, v138
	s_ashr_i32 s30, s29, 1
	s_ashr_i32 s31, s30, 31
	s_lshl_b64 s[54:55], s[30:31], 1
	v_mov_b32_e32 v139, v138
	v_mul_f32_e32 v158, 0xbfb8aa3b, v139
	v_mul_f32_e32 v112, v116, v158
	v_exp_f32_e32 v112, v112
	v_mov_b32_e32 v138, v118
	v_mul_f32_e32 v118, v118, v158
	v_exp_f32_e32 v118, v118
	v_add_f32_e32 v112, 1.0, v112
	v_rcp_f32_e32 v116, v112
	v_mul_f32_e32 v112, v117, v158
	v_exp_f32_e32 v112, v112
	v_add_f32_e32 v118, 1.0, v118
	v_rcp_f32_e32 v118, v118
	v_mov_b32_e32 v113, v139
	v_add_f32_e32 v112, 1.0, v112
	v_rcp_f32_e32 v117, v112
	v_mov_b32_e32 v112, v114
	v_pk_mul_f32 v[112:113], v[138:139], v[112:113]
	v_mul_f32_e32 v124, v124, v158
	v_mul_f32_e32 v112, v112, v113
	v_mul_f32_e32 v114, v120, v113
	v_mul_f32_e32 v120, v121, v113
	v_mul_f32_e32 v121, v122, v113
	v_mul_f32_e32 v122, v123, v113
	v_mul_f32_e32 v123, v159, v113
	v_mul_f32_e32 v118, v112, v118
	v_mul_f32_e32 v112, v119, v115
	v_exp_f32_e32 v124, v124
	v_mul_f32_e32 v125, v125, v158
	v_mul_f32_e32 v116, v123, v116
	v_mul_f32_e32 v123, v160, v113
	v_mul_f32_e32 v112, v112, v113
	v_mul_f32_e32 v113, v119, v158
	v_exp_f32_e32 v125, v125
	v_exp_f32_e32 v113, v113
	v_mul_f32_e32 v126, v126, v158
	v_exp_f32_e32 v126, v126
	v_mul_f32_e32 v127, v127, v158
	v_add_f32_e32 v124, 1.0, v124
	v_exp_f32_e32 v127, v127
	v_rcp_f32_e32 v124, v124
	v_add_f32_e32 v125, 1.0, v125
	v_add_f32_e32 v113, 1.0, v113
	v_rcp_f32_e32 v125, v125
	v_rcp_f32_e32 v113, v113
	v_add_f32_e32 v126, 1.0, v126
	v_rcp_f32_e32 v126, v126
	v_add_f32_e32 v127, 1.0, v127
	v_rcp_f32_e32 v127, v127
	v_mul_f32_e32 v114, v114, v124
	v_mul_f32_e32 v117, v123, v117
	v_mul_f32_e32 v120, v120, v125
	v_mul_f32_e32 v115, v112, v113
	v_add_u32_e32 v119, s28, v136
	v_cvt_pk_bf16_f32 v112, v114, v120
	v_cvt_pk_bf16_f32 v114, v116, v117
	v_mov_b64_e32 v[116:117], s[70:71]
	v_cvt_pk_bf16_f32 v115, v118, v115
	v_mad_i64_i32 v[118:119], s[36:37], v119, s33, v[116:117]
	v_mul_f32_e32 v121, v121, v126
	v_lshl_add_u64 v[118:119], v[118:119], 0, s[54:55]
	v_and_b32_e32 v194, 0xc0, v137
	v_mul_f32_e32 v122, v122, v127
	v_cvt_pk_bf16_f32 v113, v121, v122
	v_lshl_add_u64 v[120:121], v[118:119], 0, v[194:195]
	v_and_b32_e32 v118, 48, v137
	v_mov_b32_e32 v119, v195
	v_lshl_add_u64 v[120:121], v[120:121], 0, v[118:119]
	global_store_dwordx4 v[120:121], v[112:115], off
	v_or_b32_e32 v120, 16, v136
	v_mul_f32_e32 v100, v96, v100
	v_lshl_add_u32 v112, v120, 4, s8
	ds_read_b128 v[112:115], v112
	v_mul_f32_e32 v108, v104, v108
	v_mul_f32_e32 v109, v105, v109
	v_mul_f32_e32 v110, v106, v110
	v_mul_f32_e32 v111, v107, v111
	s_waitcnt lgkmcnt(0)
	v_mov_b32_e32 v122, v113
	v_mov_b32_e32 v123, v114
	v_mov_b32_e32 v113, v115
	v_pk_add_f32 v[112:113], v[122:123], v[112:113]
	v_mul_f32_e32 v101, v97, v101
	v_add_f32_e32 v112, v112, v113
	v_fmamk_f32 v112, v112, 0x3a800000, v189
	v_mul_f32_e32 v88, v92, v88
	v_rsq_f32_e32 v112, v112
	v_mul_f32_e32 v89, v93, v89
	v_mul_f32_e32 v90, v94, v90
	v_mul_f32_e32 v91, v95, v91
	v_mov_b32_e32 v113, v112
	v_mul_f32_e32 v114, 0xbfb8aa3b, v113
	v_mul_f32_e32 v96, v96, v114
	v_exp_f32_e32 v96, v96
	v_mul_f32_e32 v104, v104, v114
	v_exp_f32_e32 v104, v104
	v_mul_f32_e32 v105, v105, v114
	v_add_f32_e32 v96, 1.0, v96
	v_rcp_f32_e32 v115, v96
	v_mul_f32_e32 v96, v97, v114
	v_exp_f32_e32 v105, v105
	v_mul_f32_e32 v106, v106, v114
	v_exp_f32_e32 v96, v96
	v_exp_f32_e32 v106, v106
	v_mul_f32_e32 v107, v107, v114
	v_mov_b32_e32 v112, v98
	v_mul_f32_e32 v98, v98, v114
	v_exp_f32_e32 v107, v107
	v_exp_f32_e32 v98, v98
	v_add_f32_e32 v104, 1.0, v104
	v_rcp_f32_e32 v104, v104
	v_add_f32_e32 v105, 1.0, v105
	v_add_f32_e32 v96, 1.0, v96
	v_rcp_f32_e32 v105, v105
	v_add_f32_e32 v106, 1.0, v106
	v_rcp_f32_e32 v121, v96
	v_mov_b32_e32 v96, v102
	v_mov_b32_e32 v97, v113
	v_rcp_f32_e32 v106, v106
	v_add_f32_e32 v107, 1.0, v107
	v_pk_mul_f32 v[96:97], v[112:113], v[96:97]
	v_add_f32_e32 v98, 1.0, v98
	v_rcp_f32_e32 v107, v107
	v_mul_f32_e32 v102, v108, v97
	v_rcp_f32_e32 v98, v98
	v_mul_f32_e32 v102, v102, v104
	v_mul_f32_e32 v104, v109, v97
	v_mul_f32_e32 v104, v104, v105
	v_mul_f32_e32 v105, v110, v97
	v_mul_f32_e32 v105, v105, v106
	v_mul_f32_e32 v106, v111, v97
	v_mul_f32_e32 v96, v96, v97
	v_mul_f32_e32 v106, v106, v107
	v_mul_f32_e32 v107, v96, v98
	v_mul_f32_e32 v96, v99, v103
	v_mul_f32_e32 v100, v100, v97
	v_mul_f32_e32 v101, v101, v97
	v_mul_f32_e32 v96, v96, v97
	v_mul_f32_e32 v97, v99, v114
	v_exp_f32_e32 v97, v97
	v_mul_f32_e32 v100, v100, v115
	v_mul_f32_e32 v101, v101, v121
	v_add_u32_e32 v103, s28, v120
	v_add_f32_e32 v97, 1.0, v97
	v_rcp_f32_e32 v97, v97
	v_cvt_pk_bf16_f32 v98, v100, v101
	v_mad_i64_i32 v[100:101], s[30:31], v103, s33, v[116:117]
	v_lshl_add_u64 v[100:101], v[100:101], 0, s[54:55]
	v_lshl_add_u64 v[100:101], v[100:101], 0, v[194:195]
	v_mul_f32_e32 v99, v96, v97
	v_cvt_pk_bf16_f32 v96, v102, v104
	v_lshl_add_u64 v[100:101], v[100:101], 0, v[118:119]
	v_or_b32_e32 v102, 32, v136
	v_cvt_pk_bf16_f32 v97, v105, v106
	v_cvt_pk_bf16_f32 v99, v107, v99
	global_store_dwordx4 v[100:101], v[96:99], off
	v_mul_f32_e32 v68, v64, v68
	v_mul_f32_e32 v76, v72, v76
	v_lshl_add_u32 v96, v102, 4, s8
	ds_read_b128 v[96:99], v96
	v_mul_f32_e32 v77, v73, v77
	v_mul_f32_e32 v78, v74, v78
	v_mul_f32_e32 v79, v75, v79
	v_mul_f32_e32 v69, v65, v69
	s_waitcnt lgkmcnt(0)
; #define LAS __attribute__((address_space(3)))
; DEV u32x4 pack8(const float (&v)[8]) { u32x4 w; w.x = cvt_pk_bf16(v[0], v[1]); w.y = cvt_pk_bf16(v[2], v[3]); w.z = cvt_pk_bf16(v[4], v[5]); w.w = cvt_pk_bf16(v[6], v[7]); return w; }
; DEV void TileMap::operator()(int t, int& brow, int& bcol) const { int pm, pn; tile_map(t, nM, nN, pm, pn); brow = pm * 256; bcol = pn * 256; }
; DEV void TileG1::operator()(int t, int& brow, int& bcol) const { int pm, pn; tile_map(t, 192, 7, pm, pn); brow = pm * 256; bcol = (pn == 0 ? 6 : pn - 1) * 256; }
; DEV void TileMapRev::operator()(int t, int& brow, int& bcol) const { int pm, pn; tile_map(t, nM, nN, pm, pn); brow = (nM - 1 - pm) * 256; bcol = pn * 256; }
;     DEV void operator()(f32x4 (&acc)[2][2][4][2], int brow, int bcol, LAS unsigned char* lds, int par) const {
;         EPI_IDS
; #pragma unroll
;         for (int ai = 0; ai < 2; ++ai)
; #pragma unroll
;             for (int m = 0; m < 4; ++m) {
;                 const int lr = ai * 128 + wr * 64 + m * 16 + fr, row = brow + lr;
;                 const f32x4 s4 = *(const LAS f32x4*)(lds + LDS_EX + par * 4096 + lr * 16);
;                 const float rs = rsqrtf(((s4[0] + s4[1]) + (s4[2] + s4[3])) * (1.0f / 1024.0f) + EPS);
;                 float o[8];
;                 const float rs2 = rs * rs, ce = rs * -1.4426950408889634f;
; #pragma unroll
;                 for (int bj = 0; bj < 2; ++bj) {
;                     const f32x4 g = acc[ai][bj][m][0], u = acc[ai][bj][m][1];
; #pragma unroll
;                     for (int j = 0; j < 4; ++j) o[bj * 4 + j] = (g[j] * u[j]) * rs2 * __builtin_amdgcn_rcpf(1.0f + __builtin_amdgcn_exp2f(g[j] * ce));
;                 }
;                 *(u32x4*)(act + (size_t)row * DFF + (bcol >> 1) + wc * 32 + fq * 8) = pack8(o);
;             }
	v_mov_b32_e32 v100, v97
	v_mov_b32_e32 v101, v98
	v_mov_b32_e32 v97, v99
	v_pk_add_f32 v[96:97], v[100:101], v[96:97]
	v_mul_f32_e32 v99, v84, v80
	v_add_f32_e32 v96, v96, v97
	v_fmamk_f32 v96, v96, 0x3a800000, v189
	v_mul_f32_e32 v100, v85, v81
	v_rsq_f32_e32 v96, v96
	v_mul_f32_e32 v56, v60, v56
	v_mul_f32_e32 v57, v61, v57
	v_mul_f32_e32 v58, v62, v58
	v_mov_b32_e32 v97, v96
	v_mul_f32_e32 v98, 0xbfb8aa3b, v97
	v_mul_f32_e32 v80, v84, v98
	v_exp_f32_e32 v80, v80
	v_mov_b32_e32 v96, v86
	v_mul_f32_e32 v86, v86, v98
	v_exp_f32_e32 v86, v86
	v_add_f32_e32 v80, 1.0, v80
	v_rcp_f32_e32 v84, v80
	v_mul_f32_e32 v80, v85, v98
	v_exp_f32_e32 v80, v80
	v_add_f32_e32 v86, 1.0, v86
	v_rcp_f32_e32 v86, v86
	v_mov_b32_e32 v81, v97
	v_add_f32_e32 v80, 1.0, v80
	v_rcp_f32_e32 v85, v80
	v_mov_b32_e32 v80, v82
	v_pk_mul_f32 v[80:81], v[96:97], v[80:81]
	v_mul_f32_e32 v92, v92, v98
	v_mul_f32_e32 v80, v80, v81
	v_mul_f32_e32 v82, v88, v81
	v_mul_f32_e32 v88, v89, v81
	v_mul_f32_e32 v89, v90, v81
	v_mul_f32_e32 v90, v91, v81
	v_mul_f32_e32 v91, v99, v81
	v_mul_f32_e32 v86, v80, v86
	v_mul_f32_e32 v80, v87, v83
	v_exp_f32_e32 v92, v92
	v_mul_f32_e32 v93, v93, v98
	v_mul_f32_e32 v84, v91, v84
	v_mul_f32_e32 v91, v100, v81
	v_mul_f32_e32 v80, v80, v81
	v_mul_f32_e32 v81, v87, v98
	v_exp_f32_e32 v93, v93
	v_exp_f32_e32 v81, v81
	v_add_f32_e32 v92, 1.0, v92
	v_mul_f32_e32 v94, v94, v98
	v_mul_f32_e32 v95, v95, v98
	v_rcp_f32_e32 v92, v92
	v_add_f32_e32 v93, 1.0, v93
	v_exp_f32_e32 v94, v94
	v_exp_f32_e32 v95, v95
	v_add_f32_e32 v81, 1.0, v81
	v_rcp_f32_e32 v93, v93
	v_rcp_f32_e32 v81, v81
	v_add_f32_e32 v94, 1.0, v94
	v_add_f32_e32 v95, 1.0, v95
	v_mul_f32_e32 v82, v82, v92
	v_mul_f32_e32 v85, v91, v85
	v_add_u32_e32 v87, s28, v102
	v_rcp_f32_e32 v94, v94
	v_rcp_f32_e32 v95, v95
	v_mul_f32_e32 v88, v88, v93
	v_mul_f32_e32 v83, v80, v81
	v_cvt_pk_bf16_f32 v80, v82, v88
	v_cvt_pk_bf16_f32 v82, v84, v85
	v_mad_i64_i32 v[84:85], s[30:31], v87, s33, v[116:117]
	v_lshl_add_u64 v[84:85], v[84:85], 0, s[54:55]
	v_lshl_add_u64 v[84:85], v[84:85], 0, v[194:195]
	v_cvt_pk_bf16_f32 v83, v86, v83
	v_lshl_add_u64 v[84:85], v[84:85], 0, v[118:119]
	v_or_b32_e32 v86, 48, v136
	v_mul_f32_e32 v89, v89, v94
	v_mul_f32_e32 v90, v90, v95
	v_cvt_pk_bf16_f32 v81, v89, v90
	global_store_dwordx4 v[84:85], v[80:83], off
	v_mul_f32_e32 v59, v63, v59
	v_mul_f32_e32 v36, v32, v36
	v_lshl_add_u32 v80, v86, 4, s8
	ds_read_b128 v[80:83], v80
	v_mul_f32_e32 v44, v40, v44
	v_mul_f32_e32 v45, v41, v45
	v_mul_f32_e32 v46, v42, v46
	v_mul_f32_e32 v47, v43, v47
	s_waitcnt lgkmcnt(0)
	v_mov_b32_e32 v84, v81
	v_mov_b32_e32 v85, v82
	v_mov_b32_e32 v81, v83
	v_pk_add_f32 v[80:81], v[84:85], v[80:81]
	v_mul_f32_e32 v37, v33, v37
	v_add_f32_e32 v80, v80, v81
	v_fmamk_f32 v80, v80, 0x3a800000, v189
	v_mul_f32_e32 v24, v28, v24
	v_rsq_f32_e32 v80, v80
	v_mul_f32_e32 v25, v29, v25
	v_mul_f32_e32 v26, v30, v26
	v_mul_f32_e32 v27, v31, v27
	v_mov_b32_e32 v81, v80
	v_mul_f32_e32 v82, 0xbfb8aa3b, v81
	v_mul_f32_e32 v64, v64, v82
	v_exp_f32_e32 v64, v64
	v_mul_f32_e32 v72, v72, v82
	v_exp_f32_e32 v72, v72
	v_mul_f32_e32 v73, v73, v82
	v_add_f32_e32 v64, 1.0, v64
	v_rcp_f32_e32 v83, v64
	v_mul_f32_e32 v64, v65, v82
	v_exp_f32_e32 v73, v73
	v_mul_f32_e32 v74, v74, v82
	v_exp_f32_e32 v64, v64
	v_exp_f32_e32 v74, v74
	v_mul_f32_e32 v75, v75, v82
	v_mov_b32_e32 v80, v66
	v_mul_f32_e32 v66, v66, v82
	v_exp_f32_e32 v75, v75
	v_exp_f32_e32 v66, v66
	v_add_f32_e32 v72, 1.0, v72
	v_rcp_f32_e32 v72, v72
	v_add_f32_e32 v73, 1.0, v73
	v_add_f32_e32 v64, 1.0, v64
	v_rcp_f32_e32 v73, v73
	v_add_f32_e32 v74, 1.0, v74
	v_rcp_f32_e32 v84, v64
	v_mov_b32_e32 v64, v70
	v_mov_b32_e32 v65, v81
	v_rcp_f32_e32 v74, v74
	v_add_f32_e32 v75, 1.0, v75
	v_pk_mul_f32 v[64:65], v[80:81], v[64:65]
	v_add_f32_e32 v66, 1.0, v66
	v_rcp_f32_e32 v75, v75
	v_mul_f32_e32 v70, v76, v65
	v_rcp_f32_e32 v66, v66
	v_mul_f32_e32 v70, v70, v72
	v_mul_f32_e32 v72, v77, v65
	v_mul_f32_e32 v72, v72, v73
	v_mul_f32_e32 v73, v78, v65
	v_mul_f32_e32 v73, v73, v74
	v_mul_f32_e32 v74, v79, v65
	v_mul_f32_e32 v64, v64, v65
	v_mul_f32_e32 v74, v74, v75
	v_mul_f32_e32 v75, v64, v66
	v_mul_f32_e32 v64, v67, v71
	v_mul_f32_e32 v68, v68, v65
	v_mul_f32_e32 v69, v69, v65
	v_mul_f32_e32 v64, v64, v65
	v_mul_f32_e32 v65, v67, v82
	v_exp_f32_e32 v65, v65
	v_mul_f32_e32 v68, v68, v83
	v_mul_f32_e32 v69, v69, v84
	v_add_u32_e32 v71, s28, v86
	v_add_f32_e32 v65, 1.0, v65
	v_rcp_f32_e32 v65, v65
	v_cvt_pk_bf16_f32 v66, v68, v69
	v_mad_i64_i32 v[68:69], s[30:31], v71, s33, v[116:117]
	v_lshl_add_u64 v[68:69], v[68:69], 0, s[54:55]
	v_lshl_add_u64 v[68:69], v[68:69], 0, v[194:195]
	v_mul_f32_e32 v67, v64, v65
	v_cvt_pk_bf16_f32 v64, v70, v72
	v_lshl_add_u64 v[68:69], v[68:69], 0, v[118:119]
	v_add_u32_e32 v70, 0x80, v136
	v_cvt_pk_bf16_f32 v65, v73, v74
	v_cvt_pk_bf16_f32 v67, v75, v67
	global_store_dwordx4 v[68:69], v[64:67], off
	v_mul_f32_e32 v4, v0, v4
	v_mul_f32_e32 v12, v8, v12
	v_lshl_add_u32 v64, v70, 4, s8
	ds_read_b128 v[64:67], v64
	v_mul_f32_e32 v13, v9, v13
	v_mul_f32_e32 v14, v10, v14
	v_mul_f32_e32 v15, v11, v15
	v_mul_f32_e32 v5, v1, v5
	s_waitcnt lgkmcnt(0)
; #define LAS __attribute__((address_space(3)))
; DEV u32x4 pack8(const float (&v)[8]) { u32x4 w; w.x = cvt_pk_bf16(v[0], v[1]); w.y = cvt_pk_bf16(v[2], v[3]); w.z = cvt_pk_bf16(v[4], v[5]); w.w = cvt_pk_bf16(v[6], v[7]); return w; }
; DEV void TileMap::operator()(int t, int& brow, int& bcol) const { int pm, pn; tile_map(t, nM, nN, pm, pn); brow = pm * 256; bcol = pn * 256; }
; DEV void TileG1::operator()(int t, int& brow, int& bcol) const { int pm, pn; tile_map(t, 192, 7, pm, pn); brow = pm * 256; bcol = (pn == 0 ? 6 : pn - 1) * 256; }
; DEV void TileMapRev::operator()(int t, int& brow, int& bcol) const { int pm, pn; tile_map(t, nM, nN, pm, pn); brow = (nM - 1 - pm) * 256; bcol = pn * 256; }
;     DEV void operator()(f32x4 (&acc)[2][2][4][2], int brow, int bcol, LAS unsigned char* lds, int par) const {
;         EPI_IDS
; #pragma unroll
;         for (int ai = 0; ai < 2; ++ai)
; #pragma unroll
;             for (int m = 0; m < 4; ++m) {
;                 const int lr = ai * 128 + wr * 64 + m * 16 + fr, row = brow + lr;
;                 const f32x4 s4 = *(const LAS f32x4*)(lds + LDS_EX + par * 4096 + lr * 16);
;                 const float rs = rsqrtf(((s4[0] + s4[1]) + (s4[2] + s4[3])) * (1.0f / 1024.0f) + EPS);
;                 float o[8];
;                 const float rs2 = rs * rs, ce = rs * -1.4426950408889634f;
; #pragma unroll
;                 for (int bj = 0; bj < 2; ++bj) {
;                     const f32x4 g = acc[ai][bj][m][0], u = acc[ai][bj][m][1];
; #pragma unroll
;                     for (int j = 0; j < 4; ++j) o[bj * 4 + j] = (g[j] * u[j]) * rs2 * __builtin_amdgcn_rcpf(1.0f + __builtin_amdgcn_exp2f(g[j] * ce));
;                 }
;                 *(u32x4*)(act + (size_t)row * DFF + (bcol >> 1) + wc * 32 + fq * 8) = pack8(o);
;             }
	v_mov_b32_e32 v68, v65
	v_mov_b32_e32 v69, v66
	v_mov_b32_e32 v65, v67
	v_pk_add_f32 v[64:65], v[68:69], v[64:65]
	v_mul_f32_e32 v67, v52, v48
	v_add_f32_e32 v64, v64, v65
	v_fmamk_f32 v64, v64, 0x3a800000, v189
	v_mul_f32_e32 v68, v53, v49
	v_rsq_f32_e32 v64, v64
	v_readlane_b32 s97, v250, 13
	v_mov_b32_e32 v65, v64
	v_mul_f32_e32 v66, 0xbfb8aa3b, v65
	v_mul_f32_e32 v48, v52, v66
	v_exp_f32_e32 v48, v48
	v_mov_b32_e32 v64, v54
	v_mul_f32_e32 v54, v54, v66
	v_exp_f32_e32 v54, v54
	v_add_f32_e32 v48, 1.0, v48
	v_rcp_f32_e32 v52, v48
	v_mul_f32_e32 v48, v53, v66
	v_exp_f32_e32 v48, v48
	v_add_f32_e32 v54, 1.0, v54
	v_rcp_f32_e32 v54, v54
	v_mov_b32_e32 v49, v65
	v_add_f32_e32 v48, 1.0, v48
	v_rcp_f32_e32 v53, v48
	v_mov_b32_e32 v48, v50
	v_pk_mul_f32 v[48:49], v[64:65], v[48:49]
	v_mul_f32_e32 v60, v60, v66
	v_mul_f32_e32 v48, v48, v49
	v_mul_f32_e32 v50, v56, v49
	v_mul_f32_e32 v56, v57, v49
	v_mul_f32_e32 v57, v58, v49
	v_mul_f32_e32 v58, v59, v49
	v_mul_f32_e32 v59, v67, v49
	v_mul_f32_e32 v54, v48, v54
	v_mul_f32_e32 v48, v55, v51
	v_exp_f32_e32 v60, v60
	v_mul_f32_e32 v61, v61, v66
	v_mul_f32_e32 v52, v59, v52
	v_mul_f32_e32 v59, v68, v49
	v_mul_f32_e32 v48, v48, v49
	v_mul_f32_e32 v49, v55, v66
	v_exp_f32_e32 v61, v61
	v_exp_f32_e32 v49, v49
	v_add_f32_e32 v60, 1.0, v60
	v_mul_f32_e32 v62, v62, v66
	v_mul_f32_e32 v63, v63, v66
	v_rcp_f32_e32 v60, v60
	v_add_f32_e32 v61, 1.0, v61
	v_exp_f32_e32 v62, v62
	v_exp_f32_e32 v63, v63
	v_add_f32_e32 v49, 1.0, v49
	v_rcp_f32_e32 v61, v61
	v_rcp_f32_e32 v49, v49
	v_add_f32_e32 v62, 1.0, v62
	v_add_f32_e32 v63, 1.0, v63
	v_mul_f32_e32 v50, v50, v60
	v_mul_f32_e32 v53, v59, v53
	v_add_u32_e32 v55, s28, v70
	v_rcp_f32_e32 v62, v62
	v_rcp_f32_e32 v63, v63
	v_mul_f32_e32 v56, v56, v61
	v_mul_f32_e32 v51, v48, v49
	v_cvt_pk_bf16_f32 v48, v50, v56
	v_cvt_pk_bf16_f32 v50, v52, v53
	v_mad_i64_i32 v[52:53], s[30:31], v55, s33, v[116:117]
	v_lshl_add_u64 v[52:53], v[52:53], 0, s[54:55]
	v_lshl_add_u64 v[52:53], v[52:53], 0, v[194:195]
	v_cvt_pk_bf16_f32 v51, v54, v51
	v_lshl_add_u64 v[52:53], v[52:53], 0, v[118:119]
	v_add_u32_e32 v54, 0x90, v136
	v_mul_f32_e32 v57, v57, v62
	v_mul_f32_e32 v58, v58, v63
	v_cvt_pk_bf16_f32 v49, v57, v58
	global_store_dwordx4 v[52:53], v[48:51], off
	s_nop 1
	v_lshl_add_u32 v48, v54, 4, s8
	ds_read_b128 v[48:51], v48
	s_waitcnt lgkmcnt(0)
	v_mov_b32_e32 v52, v49
	v_mov_b32_e32 v53, v50
	v_mov_b32_e32 v49, v51
	v_pk_add_f32 v[48:49], v[52:53], v[48:49]
	s_nop 0
	v_add_f32_e32 v48, v48, v49
	v_fmamk_f32 v48, v48, 0x3a800000, v189
	s_nop 0
	v_rsq_f32_e32 v48, v48
	s_nop 0
	v_mov_b32_e32 v49, v48
	v_mul_f32_e32 v50, 0xbfb8aa3b, v49
	v_mul_f32_e32 v32, v32, v50
	v_exp_f32_e32 v32, v32
	v_mul_f32_e32 v40, v40, v50
	v_exp_f32_e32 v40, v40
	v_mul_f32_e32 v41, v41, v50
	v_add_f32_e32 v32, 1.0, v32
	v_rcp_f32_e32 v51, v32
	v_mul_f32_e32 v32, v33, v50
	v_exp_f32_e32 v41, v41
	v_mul_f32_e32 v42, v42, v50
	v_exp_f32_e32 v32, v32
	v_exp_f32_e32 v42, v42
	v_mul_f32_e32 v43, v43, v50
	v_mov_b32_e32 v48, v34
	v_mul_f32_e32 v34, v34, v50
	v_exp_f32_e32 v43, v43
	v_exp_f32_e32 v34, v34
	v_add_f32_e32 v40, 1.0, v40
	v_rcp_f32_e32 v40, v40
	v_add_f32_e32 v41, 1.0, v41
	v_add_f32_e32 v32, 1.0, v32
	v_rcp_f32_e32 v41, v41
	v_add_f32_e32 v42, 1.0, v42
	v_rcp_f32_e32 v52, v32
	v_mov_b32_e32 v32, v38
	v_mov_b32_e32 v33, v49
	v_rcp_f32_e32 v42, v42
	v_add_f32_e32 v43, 1.0, v43
	v_pk_mul_f32 v[32:33], v[48:49], v[32:33]
	v_add_f32_e32 v34, 1.0, v34
	v_rcp_f32_e32 v43, v43
	v_mul_f32_e32 v38, v44, v33
	v_rcp_f32_e32 v34, v34
	v_mul_f32_e32 v38, v38, v40
	v_mul_f32_e32 v40, v45, v33
	v_mul_f32_e32 v40, v40, v41
	v_mul_f32_e32 v41, v46, v33
	v_mul_f32_e32 v41, v41, v42
	v_mul_f32_e32 v42, v47, v33
	v_mul_f32_e32 v32, v32, v33
	v_mul_f32_e32 v42, v42, v43
	v_mul_f32_e32 v43, v32, v34
	v_mul_f32_e32 v32, v35, v39
	v_mul_f32_e32 v36, v36, v33
	v_mul_f32_e32 v37, v37, v33
	v_mul_f32_e32 v32, v32, v33
	v_mul_f32_e32 v33, v35, v50
	v_exp_f32_e32 v33, v33
	v_mul_f32_e32 v36, v36, v51
	v_mul_f32_e32 v37, v37, v52
	v_add_u32_e32 v39, s28, v54
	v_add_f32_e32 v33, 1.0, v33
	v_rcp_f32_e32 v33, v33
	v_cvt_pk_bf16_f32 v34, v36, v37
	v_mad_i64_i32 v[36:37], s[30:31], v39, s33, v[116:117]
	v_lshl_add_u64 v[36:37], v[36:37], 0, s[54:55]
	v_lshl_add_u64 v[36:37], v[36:37], 0, v[194:195]
	v_mul_f32_e32 v35, v32, v33
	v_cvt_pk_bf16_f32 v32, v38, v40
	v_lshl_add_u64 v[36:37], v[36:37], 0, v[118:119]
	v_add_u32_e32 v38, 0xa0, v136
	v_cvt_pk_bf16_f32 v33, v41, v42
	v_cvt_pk_bf16_f32 v35, v43, v35
	global_store_dwordx4 v[36:37], v[32:35], off
	s_nop 1
	v_lshl_add_u32 v32, v38, 4, s8
	ds_read_b128 v[32:35], v32
	s_waitcnt lgkmcnt(0)
; #define LAS __attribute__((address_space(3)))
; DEV u32x4 pack8(const float (&v)[8]) { u32x4 w; w.x = cvt_pk_bf16(v[0], v[1]); w.y = cvt_pk_bf16(v[2], v[3]); w.z = cvt_pk_bf16(v[4], v[5]); w.w = cvt_pk_bf16(v[6], v[7]); return w; }
; #define BAR __builtin_amdgcn_s_barrier()
; DEV void TileMap::operator()(int t, int& brow, int& bcol) const { int pm, pn; tile_map(t, nM, nN, pm, pn); brow = pm * 256; bcol = pn * 256; }
; DEV void TileMapRev::operator()(int t, int& brow, int& bcol) const { int pm, pn; tile_map(t, nM, nN, pm, pn); brow = (nM - 1 - pm) * 256; bcol = pn * 256; }
; template <int BMODE, class Epi, class TileFn>
; DEV void gemm_loop(LAS unsigned char* lds, const bf16_t* __restrict__ A, int lda, const bf16_t* __restrict__ B, int ldb, int K, const Epi& epi, int t0, int tstep, int tend, const TileFn& tf) {
;     ...
;         if (wr == 0) BAR;
;         epi(acc, brow, bcol, lds, par);
;         if (!has_next) break;
; #pragma unroll
;         for (int a = 0; a < 2; ++a)
; #pragma unroll
;             for (int b = 0; b < 2; ++b)
; #pragma unroll
;                 for (int m = 0; m < 4; ++m)
; #pragma unroll
;                     for (int n = 0; n < 2; ++n) acc[a][b][m][n] = (f32x4){0.f, 0.f, 0.f, 0.f};
;         brow = nrow; bcol = ncol; cA = nA; cB = nB;
;         if (wr == 1) BAR;
;     }
;     DEV void operator()(f32x4 (&acc)[2][2][4][2], int brow, int bcol, LAS unsigned char* lds, int par) const {
;         EPI_IDS
; #pragma unroll
;         for (int ai = 0; ai < 2; ++ai)
; #pragma unroll
;             for (int m = 0; m < 4; ++m) {
;                 const int lr = ai * 128 + wr * 64 + m * 16 + fr, row = brow + lr;
;                 const f32x4 s4 = *(const LAS f32x4*)(lds + LDS_EX + par * 4096 + lr * 16);
;                 const float rs = rsqrtf(((s4[0] + s4[1]) + (s4[2] + s4[3])) * (1.0f / 1024.0f) + EPS);
;                 float o[8];
;                 const float rs2 = rs * rs, ce = rs * -1.4426950408889634f;
; #pragma unroll
;                 for (int bj = 0; bj < 2; ++bj) {
;                     const f32x4 g = acc[ai][bj][m][0], u = acc[ai][bj][m][1];
; #pragma unroll
;                     for (int j = 0; j < 4; ++j) o[bj * 4 + j] = (g[j] * u[j]) * rs2 * __builtin_amdgcn_rcpf(1.0f + __builtin_amdgcn_exp2f(g[j] * ce));
;                 }
;                 *(u32x4*)(act + (size_t)row * DFF + (bcol >> 1) + wc * 32 + fq * 8) = pack8(o);
;             }
	v_mov_b32_e32 v36, v33
	v_mov_b32_e32 v37, v34
	v_mov_b32_e32 v33, v35
	v_pk_add_f32 v[32:33], v[36:37], v[32:33]
	v_mul_f32_e32 v35, v20, v16
	v_add_f32_e32 v32, v32, v33
	v_fmamk_f32 v32, v32, 0x3a800000, v189
	v_mul_f32_e32 v36, v21, v17
	v_rsq_f32_e32 v32, v32
	s_nop 0
	v_mov_b32_e32 v33, v32
	v_mul_f32_e32 v34, 0xbfb8aa3b, v33
	v_mul_f32_e32 v16, v20, v34
	v_exp_f32_e32 v16, v16
	v_mov_b32_e32 v32, v22
	v_mul_f32_e32 v22, v22, v34
	v_exp_f32_e32 v22, v22
	v_add_f32_e32 v16, 1.0, v16
	v_rcp_f32_e32 v20, v16
	v_mul_f32_e32 v16, v21, v34
	v_exp_f32_e32 v16, v16
	v_add_f32_e32 v22, 1.0, v22
	v_rcp_f32_e32 v22, v22
	v_mov_b32_e32 v17, v33
	v_add_f32_e32 v16, 1.0, v16
	v_rcp_f32_e32 v21, v16
	v_mov_b32_e32 v16, v18
	v_pk_mul_f32 v[16:17], v[32:33], v[16:17]
	v_mul_f32_e32 v28, v28, v34
	v_mul_f32_e32 v16, v16, v17
	v_mul_f32_e32 v18, v24, v17
	v_mul_f32_e32 v24, v25, v17
	v_mul_f32_e32 v25, v26, v17
	v_mul_f32_e32 v26, v27, v17
	v_mul_f32_e32 v27, v35, v17
	v_mul_f32_e32 v22, v16, v22
	v_mul_f32_e32 v16, v23, v19
	v_exp_f32_e32 v28, v28
	v_mul_f32_e32 v29, v29, v34
	v_mul_f32_e32 v20, v27, v20
	v_mul_f32_e32 v27, v36, v17
	v_mul_f32_e32 v16, v16, v17
	v_mul_f32_e32 v17, v23, v34
	v_exp_f32_e32 v29, v29
	v_exp_f32_e32 v17, v17
	v_add_f32_e32 v28, 1.0, v28
	v_mul_f32_e32 v30, v30, v34
	v_mul_f32_e32 v31, v31, v34
	v_rcp_f32_e32 v28, v28
	v_add_f32_e32 v29, 1.0, v29
	v_exp_f32_e32 v30, v30
	v_exp_f32_e32 v31, v31
	v_add_f32_e32 v17, 1.0, v17
	v_rcp_f32_e32 v29, v29
	v_rcp_f32_e32 v17, v17
	v_add_f32_e32 v30, 1.0, v30
	v_add_f32_e32 v31, 1.0, v31
	v_mul_f32_e32 v18, v18, v28
	v_mul_f32_e32 v21, v27, v21
	v_add_u32_e32 v23, s28, v38
	v_rcp_f32_e32 v30, v30
	v_rcp_f32_e32 v31, v31
	v_mul_f32_e32 v24, v24, v29
	v_mul_f32_e32 v19, v16, v17
	v_cvt_pk_bf16_f32 v16, v18, v24
	v_cvt_pk_bf16_f32 v18, v20, v21
	v_mad_i64_i32 v[20:21], s[30:31], v23, s33, v[116:117]
	v_lshl_add_u64 v[20:21], v[20:21], 0, s[54:55]
	v_lshl_add_u64 v[20:21], v[20:21], 0, v[194:195]
	v_cvt_pk_bf16_f32 v19, v22, v19
	v_lshl_add_u64 v[20:21], v[20:21], 0, v[118:119]
	v_add_u32_e32 v22, 0xb0, v136
	v_mul_f32_e32 v25, v25, v30
	v_mul_f32_e32 v26, v26, v31
	v_cvt_pk_bf16_f32 v17, v25, v26
	global_store_dwordx4 v[20:21], v[16:19], off
	s_nop 1
	v_lshl_add_u32 v16, v22, 4, s8
	ds_read_b128 v[16:19], v16
	s_waitcnt lgkmcnt(0)
	v_mov_b32_e32 v20, v17
	v_mov_b32_e32 v21, v18
	v_mov_b32_e32 v17, v19
	v_pk_add_f32 v[16:17], v[20:21], v[16:17]
	s_nop 0
	v_add_f32_e32 v16, v16, v17
	v_fmamk_f32 v16, v16, 0x3a800000, v189
	s_nop 0
	v_rsq_f32_e32 v16, v16
	s_nop 0
	v_mov_b32_e32 v17, v16
	v_mul_f32_e32 v18, 0xbfb8aa3b, v17
	v_mul_f32_e32 v0, v0, v18
	v_exp_f32_e32 v0, v0
	v_mul_f32_e32 v8, v8, v18
	v_exp_f32_e32 v8, v8
	v_mul_f32_e32 v9, v9, v18
	v_add_f32_e32 v0, 1.0, v0
	v_rcp_f32_e32 v19, v0
	v_mul_f32_e32 v0, v1, v18
	v_exp_f32_e32 v9, v9
	v_mul_f32_e32 v10, v10, v18
	v_exp_f32_e32 v0, v0
	v_exp_f32_e32 v10, v10
	v_mul_f32_e32 v11, v11, v18
	v_mov_b32_e32 v16, v2
	v_mul_f32_e32 v2, v2, v18
	v_exp_f32_e32 v11, v11
	v_exp_f32_e32 v2, v2
	v_add_f32_e32 v8, 1.0, v8
	v_rcp_f32_e32 v8, v8
	v_add_f32_e32 v9, 1.0, v9
	v_add_f32_e32 v0, 1.0, v0
	v_rcp_f32_e32 v9, v9
	v_add_f32_e32 v10, 1.0, v10
	v_rcp_f32_e32 v20, v0
	v_mov_b32_e32 v0, v6
	v_mov_b32_e32 v1, v17
	v_rcp_f32_e32 v10, v10
	v_add_f32_e32 v11, 1.0, v11
	v_pk_mul_f32 v[0:1], v[16:17], v[0:1]
	v_add_f32_e32 v2, 1.0, v2
	v_rcp_f32_e32 v11, v11
	v_mul_f32_e32 v6, v12, v1
	v_rcp_f32_e32 v2, v2
	v_mul_f32_e32 v6, v6, v8
	v_mul_f32_e32 v8, v13, v1
	v_mul_f32_e32 v8, v8, v9
	v_mul_f32_e32 v9, v14, v1
	v_mul_f32_e32 v9, v9, v10
	v_mul_f32_e32 v10, v15, v1
	v_mul_f32_e32 v0, v0, v1
	v_mul_f32_e32 v10, v10, v11
	v_mul_f32_e32 v11, v0, v2
	v_mul_f32_e32 v0, v3, v7
	v_mul_f32_e32 v4, v4, v1
	v_mul_f32_e32 v5, v5, v1
	v_mul_f32_e32 v0, v0, v1
	v_mul_f32_e32 v1, v3, v18
	v_exp_f32_e32 v1, v1
	v_mul_f32_e32 v4, v4, v19
	v_mul_f32_e32 v5, v5, v20
	v_add_u32_e32 v7, s28, v22
	v_add_f32_e32 v1, 1.0, v1
	v_rcp_f32_e32 v1, v1
	v_cvt_pk_bf16_f32 v2, v4, v5
	v_mad_i64_i32 v[4:5], s[8:9], v7, s33, v[116:117]
	v_lshl_add_u64 v[4:5], v[4:5], 0, s[54:55]
	v_lshl_add_u64 v[4:5], v[4:5], 0, v[194:195]
	v_mul_f32_e32 v3, v0, v1
	v_lshl_add_u64 v[4:5], v[4:5], 0, v[118:119]
	s_mov_b64 s[8:9], -1
	s_andn2_b64 vcc, exec, s[76:77]
	v_cvt_pk_bf16_f32 v0, v6, v8
	v_cvt_pk_bf16_f32 v1, v9, v10
	v_cvt_pk_bf16_f32 v3, v11, v3
	global_store_dwordx4 v[4:5], v[0:3], off
	s_cbranch_vccnz .LBB0_1332
	s_and_saveexec_b64 s[8:9], s[38:39]
	s_cbranch_execz .LBB0_1331
	s_barrier
	s_branch .LBB0_1331
